# all four live 8-phase K loops: LDS-DMA loads in saddr form, no per-load 64-bit VALU adds
# speedup vs baseline: 1.0146x; 1.0060x over previous
.LBB0_234:
	v_mov_b32_e32 v129, 0
	s_andn2_b64 vcc, exec, s[24:25]
	v_mov_b32_e32 v128, v129
	v_mov_b32_e32 v127, v129
	v_mov_b32_e32 v126, v129
	v_mov_b32_e32 v125, v129
	v_mov_b32_e32 v124, v129
	v_mov_b32_e32 v123, v129
	v_mov_b32_e32 v122, v129
	v_mov_b32_e32 v113, v129
	v_mov_b32_e32 v112, v129
	v_mov_b32_e32 v111, v129
	v_mov_b32_e32 v110, v129
	v_mov_b32_e32 v109, v129
	v_mov_b32_e32 v108, v129
	v_mov_b32_e32 v107, v129
	v_mov_b32_e32 v106, v129
	v_mov_b32_e32 v97, v129
	v_mov_b32_e32 v96, v129
	v_mov_b32_e32 v95, v129
	v_mov_b32_e32 v94, v129
	v_mov_b32_e32 v93, v129
	v_mov_b32_e32 v92, v129
	v_mov_b32_e32 v91, v129
	v_mov_b32_e32 v90, v129
	v_mov_b32_e32 v81, v129
	v_mov_b32_e32 v80, v129
	v_mov_b32_e32 v79, v129
	v_mov_b32_e32 v78, v129
	v_mov_b32_e32 v77, v129
	v_mov_b32_e32 v76, v129
	v_mov_b32_e32 v75, v129
	v_mov_b32_e32 v74, v129
	v_mov_b32_e32 v121, v129
	v_mov_b32_e32 v120, v129
	v_mov_b32_e32 v119, v129
	v_mov_b32_e32 v118, v129
	v_mov_b32_e32 v117, v129
	v_mov_b32_e32 v116, v129
	v_mov_b32_e32 v115, v129
	v_mov_b32_e32 v114, v129
	v_mov_b32_e32 v105, v129
	v_mov_b32_e32 v104, v129
	v_mov_b32_e32 v103, v129
	v_mov_b32_e32 v102, v129
	v_mov_b32_e32 v101, v129
	v_mov_b32_e32 v100, v129
	v_mov_b32_e32 v99, v129
	v_mov_b32_e32 v98, v129
	v_mov_b32_e32 v89, v129
	v_mov_b32_e32 v88, v129
	v_mov_b32_e32 v87, v129
	v_mov_b32_e32 v86, v129
	v_mov_b32_e32 v85, v129
	v_mov_b32_e32 v84, v129
	v_mov_b32_e32 v83, v129
	v_mov_b32_e32 v82, v129
	v_mov_b32_e32 v73, v129
	v_mov_b32_e32 v72, v129
	v_mov_b32_e32 v71, v129
	v_mov_b32_e32 v70, v129
	v_mov_b32_e32 v69, v129
	v_mov_b32_e32 v68, v129
	v_mov_b32_e32 v67, v129
	v_mov_b32_e32 v66, v129
	v_mov_b32_e32 v65, v129
	v_mov_b32_e32 v64, v129
	v_mov_b32_e32 v63, v129
	v_mov_b32_e32 v62, v129
	v_mov_b32_e32 v61, v129
	v_mov_b32_e32 v60, v129
	v_mov_b32_e32 v59, v129
	v_mov_b32_e32 v58, v129
	v_mov_b32_e32 v49, v129
	v_mov_b32_e32 v48, v129
	v_mov_b32_e32 v47, v129
	v_mov_b32_e32 v46, v129
	v_mov_b32_e32 v45, v129
	v_mov_b32_e32 v44, v129
	v_mov_b32_e32 v43, v129
	v_mov_b32_e32 v42, v129
	v_mov_b32_e32 v33, v129
	v_mov_b32_e32 v32, v129
	v_mov_b32_e32 v31, v129
	v_mov_b32_e32 v30, v129
	v_mov_b32_e32 v29, v129
	v_mov_b32_e32 v28, v129
	v_mov_b32_e32 v27, v129
	v_mov_b32_e32 v26, v129
	v_mov_b32_e32 v17, v129
	v_mov_b32_e32 v16, v129
	v_mov_b32_e32 v15, v129
	v_mov_b32_e32 v14, v129
	v_mov_b32_e32 v13, v129
	v_mov_b32_e32 v12, v129
	v_mov_b32_e32 v11, v129
	v_mov_b32_e32 v10, v129
	v_mov_b32_e32 v57, v129
	v_mov_b32_e32 v56, v129
	v_mov_b32_e32 v55, v129
	v_mov_b32_e32 v54, v129
	v_mov_b32_e32 v53, v129
	v_mov_b32_e32 v52, v129
	v_mov_b32_e32 v51, v129
	v_mov_b32_e32 v50, v129
	v_mov_b32_e32 v41, v129
	v_mov_b32_e32 v40, v129
	v_mov_b32_e32 v39, v129
	v_mov_b32_e32 v38, v129
	v_mov_b32_e32 v37, v129
	v_mov_b32_e32 v36, v129
	v_mov_b32_e32 v35, v129
	v_mov_b32_e32 v34, v129
	v_mov_b32_e32 v25, v129
	v_mov_b32_e32 v24, v129
	v_mov_b32_e32 v23, v129
	v_mov_b32_e32 v22, v129
	v_mov_b32_e32 v21, v129
	v_mov_b32_e32 v20, v129
	v_mov_b32_e32 v19, v129
	v_mov_b32_e32 v18, v129
	v_mov_b32_e32 v9, v129
	v_mov_b32_e32 v8, v129
	v_mov_b32_e32 v7, v129
	v_mov_b32_e32 v6, v129
	v_mov_b32_e32 v5, v129
	v_mov_b32_e32 v4, v129
	v_mov_b32_e32 v3, v129
	v_mov_b32_e32 v2, v129
	s_cbranch_vccnz .LBB0_237
	s_add_u32 s6, s10, 0x80
	s_addc_u32 s7, s11, 0
	s_add_u32 s10, s8, 0x100
	v_mov_b32_e32 v2, 0
	s_addc_u32 s11, s9, 0
	s_mov_b32 s2, 0
	v_mov_b32_e32 v3, v2
	v_mov_b32_e32 v4, v2
	v_mov_b32_e32 v5, v2
	v_mov_b32_e32 v6, v2
	v_mov_b32_e32 v7, v2
	v_mov_b32_e32 v8, v2
	v_mov_b32_e32 v9, v2
	v_mov_b32_e32 v18, v2
	v_mov_b32_e32 v19, v2
	v_mov_b32_e32 v20, v2
	v_mov_b32_e32 v21, v2
	v_mov_b32_e32 v22, v2
	v_mov_b32_e32 v23, v2
	v_mov_b32_e32 v24, v2
	v_mov_b32_e32 v25, v2
	v_mov_b32_e32 v34, v2
	v_mov_b32_e32 v35, v2
	v_mov_b32_e32 v36, v2
	v_mov_b32_e32 v37, v2
	v_mov_b32_e32 v38, v2
	v_mov_b32_e32 v39, v2
	v_mov_b32_e32 v40, v2
	v_mov_b32_e32 v41, v2
	v_mov_b32_e32 v50, v2
	v_mov_b32_e32 v51, v2
	v_mov_b32_e32 v52, v2
	v_mov_b32_e32 v53, v2
	v_mov_b32_e32 v54, v2
	v_mov_b32_e32 v55, v2
	v_mov_b32_e32 v56, v2
	v_mov_b32_e32 v57, v2
	v_mov_b32_e32 v10, v2
	v_mov_b32_e32 v11, v2
	v_mov_b32_e32 v12, v2
	v_mov_b32_e32 v13, v2
	v_mov_b32_e32 v14, v2
	v_mov_b32_e32 v15, v2
	v_mov_b32_e32 v16, v2
	v_mov_b32_e32 v17, v2
	v_mov_b32_e32 v26, v2
	v_mov_b32_e32 v27, v2
	v_mov_b32_e32 v28, v2
	v_mov_b32_e32 v29, v2
	v_mov_b32_e32 v30, v2
	v_mov_b32_e32 v31, v2
	v_mov_b32_e32 v32, v2
	v_mov_b32_e32 v33, v2
	v_mov_b32_e32 v42, v2
	v_mov_b32_e32 v43, v2
	v_mov_b32_e32 v44, v2
	v_mov_b32_e32 v45, v2
	v_mov_b32_e32 v46, v2
	v_mov_b32_e32 v47, v2
	v_mov_b32_e32 v48, v2
	v_mov_b32_e32 v49, v2
	v_mov_b32_e32 v58, v2
	v_mov_b32_e32 v59, v2
	v_mov_b32_e32 v60, v2
	v_mov_b32_e32 v61, v2
	v_mov_b32_e32 v62, v2
	v_mov_b32_e32 v63, v2
	v_mov_b32_e32 v64, v2
	v_mov_b32_e32 v65, v2
	v_mov_b32_e32 v66, v2
	v_mov_b32_e32 v67, v2
	v_mov_b32_e32 v68, v2
	v_mov_b32_e32 v69, v2
	v_mov_b32_e32 v70, v2
	v_mov_b32_e32 v71, v2
	v_mov_b32_e32 v72, v2
	v_mov_b32_e32 v73, v2
	v_mov_b32_e32 v82, v2
	v_mov_b32_e32 v83, v2
	v_mov_b32_e32 v84, v2
	v_mov_b32_e32 v85, v2
	v_mov_b32_e32 v86, v2
	v_mov_b32_e32 v87, v2
	v_mov_b32_e32 v88, v2
	v_mov_b32_e32 v89, v2
	v_mov_b32_e32 v98, v2
	v_mov_b32_e32 v99, v2
	v_mov_b32_e32 v100, v2
	v_mov_b32_e32 v101, v2
	v_mov_b32_e32 v102, v2
	v_mov_b32_e32 v103, v2
	v_mov_b32_e32 v104, v2
	v_mov_b32_e32 v105, v2
	v_mov_b32_e32 v114, v2
	v_mov_b32_e32 v115, v2
	v_mov_b32_e32 v116, v2
	v_mov_b32_e32 v117, v2
	v_mov_b32_e32 v118, v2
	v_mov_b32_e32 v119, v2
	v_mov_b32_e32 v120, v2
	v_mov_b32_e32 v121, v2
	v_mov_b32_e32 v74, v2
	v_mov_b32_e32 v75, v2
	v_mov_b32_e32 v76, v2
	v_mov_b32_e32 v77, v2
	v_mov_b32_e32 v78, v2
	v_mov_b32_e32 v79, v2
	v_mov_b32_e32 v80, v2
	v_mov_b32_e32 v81, v2
	v_mov_b32_e32 v90, v2
	v_mov_b32_e32 v91, v2
	v_mov_b32_e32 v92, v2
	v_mov_b32_e32 v93, v2
	v_mov_b32_e32 v94, v2
	v_mov_b32_e32 v95, v2
	v_mov_b32_e32 v96, v2
	v_mov_b32_e32 v97, v2
	v_mov_b32_e32 v106, v2
	v_mov_b32_e32 v107, v2
	v_mov_b32_e32 v108, v2
	v_mov_b32_e32 v109, v2
	v_mov_b32_e32 v110, v2
	v_mov_b32_e32 v111, v2
	v_mov_b32_e32 v112, v2
	v_mov_b32_e32 v113, v2
	v_mov_b32_e32 v122, v2
	v_mov_b32_e32 v123, v2
	v_mov_b32_e32 v124, v2
	v_mov_b32_e32 v125, v2
	v_mov_b32_e32 v126, v2
	v_mov_b32_e32 v127, v2
	v_mov_b32_e32 v128, v2
	v_mov_b32_e32 v129, v2
	v_add_u32_e32 v243, s18, v130
	v_add_u32_e32 v242, s18, v132
.LBB0_236:
	ds_read_b128 v[144:147], v160
	ds_read_b128 v[148:151], v161
	ds_read_b128 v[178:181], v163
	ds_read_b128 v[182:185], v164
	s_add_i32 s14, s2, 2
	s_add_u32 s8, s6, 0x80
	s_addc_u32 s3, s7, 0
	s_cmp_eq_u32 s56, s2
	s_cselect_b32 s2, s62, s8
	s_cselect_b32 s3, s63, s3
	s_cselect_b32 s9, s1, s11
	s_cselect_b32 s8, s0, s10
	s_mov_b32 m0, s61
	ds_read_b128 v[186:189], v158
	ds_read_b128 v[190:193], v158 offset:1024
	ds_read_b128 v[194:197], v158 offset:2048
	ds_read_b128 v[198:201], v158 offset:3072
	ds_read_b128 v[202:205], v158 offset:4096
	ds_read_b128 v[206:209], v158 offset:5120
	ds_read_b128 v[210:213], v158 offset:6144
	ds_read_b128 v[214:217], v158 offset:7168
	global_load_lds_dwordx4 v136, s[6:7]
	s_mov_b32 m0, s64
	s_nop 0
	global_load_lds_dwordx4 v138, s[6:7]
	s_waitcnt lgkmcnt(8)
	s_barrier
	s_waitcnt lgkmcnt(0)
	s_waitcnt lgkmcnt(0)
	v_mfma_f32_16x16x32_bf16 v[126:129], v[144:147], v[186:189], v[126:129]
	v_mfma_f32_16x16x32_bf16 v[122:125], v[178:181], v[186:189], v[122:125]
	v_mfma_f32_16x16x32_bf16 v[110:113], v[144:147], v[194:197], v[110:113]
	v_mfma_f32_16x16x32_bf16 v[106:109], v[178:181], v[194:197], v[106:109]
	v_mfma_f32_16x16x32_bf16 v[94:97], v[144:147], v[202:205], v[94:97]
	v_mfma_f32_16x16x32_bf16 v[90:93], v[178:181], v[202:205], v[90:93]
	v_mfma_f32_16x16x32_bf16 v[78:81], v[144:147], v[210:213], v[78:81]
	v_mfma_f32_16x16x32_bf16 v[74:77], v[178:181], v[210:213], v[74:77]
	v_mfma_f32_16x16x32_bf16 v[126:129], v[148:151], v[190:193], v[126:129]
	v_mfma_f32_16x16x32_bf16 v[122:125], v[182:185], v[190:193], v[122:125]
	v_mfma_f32_16x16x32_bf16 v[110:113], v[148:151], v[198:201], v[110:113]
	v_mfma_f32_16x16x32_bf16 v[106:109], v[182:185], v[198:201], v[106:109]
	v_mfma_f32_16x16x32_bf16 v[94:97], v[148:151], v[206:209], v[94:97]
	v_mfma_f32_16x16x32_bf16 v[90:93], v[182:185], v[206:209], v[90:93]
	v_mfma_f32_16x16x32_bf16 v[78:81], v[148:151], v[214:217], v[78:81]
	v_mfma_f32_16x16x32_bf16 v[74:77], v[182:185], v[214:217], v[74:77]
	s_barrier
	s_mov_b32 m0, s30
	ds_read_b128 v[218:221], v165
	ds_read_b128 v[222:225], v166
	ds_read_b128 v[226:229], v167
	ds_read_b128 v[230:233], v168
	global_load_lds_dwordx4 v130, s[8:9]
	s_mov_b32 m0, s31
	s_nop 0
	global_load_lds_dwordx4 v132, s[8:9]
	s_barrier
	s_waitcnt lgkmcnt(0)
	s_waitcnt lgkmcnt(0)
	v_mfma_f32_16x16x32_bf16 v[118:121], v[218:221], v[186:189], v[118:121]
	v_mfma_f32_16x16x32_bf16 v[114:117], v[226:229], v[186:189], v[114:117]
	v_mfma_f32_16x16x32_bf16 v[102:105], v[218:221], v[194:197], v[102:105]
	v_mfma_f32_16x16x32_bf16 v[98:101], v[226:229], v[194:197], v[98:101]
	v_mfma_f32_16x16x32_bf16 v[86:89], v[218:221], v[202:205], v[86:89]
	v_mfma_f32_16x16x32_bf16 v[82:85], v[226:229], v[202:205], v[82:85]
	v_mfma_f32_16x16x32_bf16 v[70:73], v[218:221], v[210:213], v[70:73]
	v_mfma_f32_16x16x32_bf16 v[66:69], v[226:229], v[210:213], v[66:69]
	v_mfma_f32_16x16x32_bf16 v[118:121], v[222:225], v[190:193], v[118:121]
	v_mfma_f32_16x16x32_bf16 v[114:117], v[230:233], v[190:193], v[114:117]
	v_mfma_f32_16x16x32_bf16 v[102:105], v[222:225], v[198:201], v[102:105]
	v_mfma_f32_16x16x32_bf16 v[98:101], v[230:233], v[198:201], v[98:101]
	v_mfma_f32_16x16x32_bf16 v[86:89], v[222:225], v[206:209], v[86:89]
	v_mfma_f32_16x16x32_bf16 v[82:85], v[230:233], v[206:209], v[82:85]
	v_mfma_f32_16x16x32_bf16 v[70:73], v[222:225], v[214:217], v[70:73]
	v_mfma_f32_16x16x32_bf16 v[66:69], v[230:233], v[214:217], v[66:69]
	s_mov_b32 m0, s29
	s_barrier
	ds_read_b128 v[186:189], v158 offset:16384
	ds_read_b128 v[190:193], v158 offset:17408
	ds_read_b128 v[194:197], v158 offset:18432
	ds_read_b128 v[198:201], v158 offset:19456
	ds_read_b128 v[202:205], v158 offset:20480
	ds_read_b128 v[206:209], v158 offset:21504
	ds_read_b128 v[210:213], v158 offset:22528
	ds_read_b128 v[214:217], v158 offset:23552
	global_load_lds_dwordx4 v130, s[2:3]
	s_mov_b32 m0, s33
	s_nop 0
	global_load_lds_dwordx4 v132, s[2:3]
	s_barrier
	s_waitcnt lgkmcnt(0)
	s_waitcnt lgkmcnt(0)
	v_mfma_f32_16x16x32_bf16 v[62:65], v[144:147], v[186:189], v[62:65]
	v_mfma_f32_16x16x32_bf16 v[58:61], v[178:181], v[186:189], v[58:61]
	v_mfma_f32_16x16x32_bf16 v[46:49], v[144:147], v[194:197], v[46:49]
	v_mfma_f32_16x16x32_bf16 v[42:45], v[178:181], v[194:197], v[42:45]
	v_mfma_f32_16x16x32_bf16 v[30:33], v[144:147], v[202:205], v[30:33]
	v_mfma_f32_16x16x32_bf16 v[26:29], v[178:181], v[202:205], v[26:29]
	v_mfma_f32_16x16x32_bf16 v[14:17], v[144:147], v[210:213], v[14:17]
	v_mfma_f32_16x16x32_bf16 v[10:13], v[178:181], v[210:213], v[10:13]
	v_mfma_f32_16x16x32_bf16 v[62:65], v[148:151], v[190:193], v[62:65]
	v_mfma_f32_16x16x32_bf16 v[58:61], v[182:185], v[190:193], v[58:61]
	v_mfma_f32_16x16x32_bf16 v[46:49], v[148:151], v[198:201], v[46:49]
	v_mfma_f32_16x16x32_bf16 v[42:45], v[182:185], v[198:201], v[42:45]
	v_mfma_f32_16x16x32_bf16 v[30:33], v[148:151], v[206:209], v[30:33]
	v_mfma_f32_16x16x32_bf16 v[26:29], v[182:185], v[206:209], v[26:29]
	v_mfma_f32_16x16x32_bf16 v[14:17], v[148:151], v[214:217], v[14:17]
	v_mfma_f32_16x16x32_bf16 v[10:13], v[182:185], v[214:217], v[10:13]
	s_barrier
	s_mov_b32 m0, s34
	s_nop 0
	global_load_lds_dwordx4 v243, s[8:9]
	s_mov_b32 m0, s35
	s_nop 0
	global_load_lds_dwordx4 v242, s[8:9]
	s_waitcnt vmcnt(6)
	s_barrier
	v_mfma_f32_16x16x32_bf16 v[54:57], v[218:221], v[186:189], v[54:57]
	v_mfma_f32_16x16x32_bf16 v[50:53], v[226:229], v[186:189], v[50:53]
	v_mfma_f32_16x16x32_bf16 v[38:41], v[218:221], v[194:197], v[38:41]
	v_mfma_f32_16x16x32_bf16 v[34:37], v[226:229], v[194:197], v[34:37]
	v_mfma_f32_16x16x32_bf16 v[22:25], v[218:221], v[202:205], v[22:25]
	v_mfma_f32_16x16x32_bf16 v[18:21], v[226:229], v[202:205], v[18:21]
	v_mfma_f32_16x16x32_bf16 v[6:9], v[218:221], v[210:213], v[6:9]
	v_mfma_f32_16x16x32_bf16 v[2:5], v[226:229], v[210:213], v[2:5]
	v_mfma_f32_16x16x32_bf16 v[54:57], v[222:225], v[190:193], v[54:57]
	v_mfma_f32_16x16x32_bf16 v[50:53], v[230:233], v[190:193], v[50:53]
	v_mfma_f32_16x16x32_bf16 v[38:41], v[222:225], v[198:201], v[38:41]
	v_mfma_f32_16x16x32_bf16 v[34:37], v[230:233], v[198:201], v[34:37]
	v_mfma_f32_16x16x32_bf16 v[22:25], v[222:225], v[206:209], v[22:25]
	v_mfma_f32_16x16x32_bf16 v[18:21], v[230:233], v[206:209], v[18:21]
	v_mfma_f32_16x16x32_bf16 v[6:9], v[222:225], v[214:217], v[6:9]
	v_mfma_f32_16x16x32_bf16 v[2:5], v[230:233], v[214:217], v[2:5]
	s_barrier
	ds_read_b128 v[144:147], v169
	ds_read_b128 v[148:151], v170
	ds_read_b128 v[178:181], v171
	ds_read_b128 v[182:185], v172
	s_mov_b32 m0, s38
	ds_read_b128 v[186:189], v158 offset:32768
	ds_read_b128 v[190:193], v158 offset:33792
	ds_read_b128 v[194:197], v158 offset:34816
	ds_read_b128 v[198:201], v158 offset:35840
	ds_read_b128 v[202:205], v158 offset:36864
	ds_read_b128 v[206:209], v158 offset:37888
	ds_read_b128 v[210:213], v158 offset:38912
	ds_read_b128 v[214:217], v158 offset:39936
	global_load_lds_dwordx4 v243, s[2:3]
	s_mov_b32 m0, s39
	s_nop 0
	global_load_lds_dwordx4 v242, s[2:3]
	s_waitcnt lgkmcnt(8)
	s_barrier
	s_waitcnt lgkmcnt(0)
	s_waitcnt lgkmcnt(0)
	v_mfma_f32_16x16x32_bf16 v[126:129], v[144:147], v[186:189], v[126:129]
	v_mfma_f32_16x16x32_bf16 v[122:125], v[178:181], v[186:189], v[122:125]
	v_mfma_f32_16x16x32_bf16 v[110:113], v[144:147], v[194:197], v[110:113]
	v_mfma_f32_16x16x32_bf16 v[106:109], v[178:181], v[194:197], v[106:109]
	v_mfma_f32_16x16x32_bf16 v[94:97], v[144:147], v[202:205], v[94:97]
	v_mfma_f32_16x16x32_bf16 v[90:93], v[178:181], v[202:205], v[90:93]
	v_mfma_f32_16x16x32_bf16 v[78:81], v[144:147], v[210:213], v[78:81]
	v_mfma_f32_16x16x32_bf16 v[74:77], v[178:181], v[210:213], v[74:77]
	v_mfma_f32_16x16x32_bf16 v[126:129], v[148:151], v[190:193], v[126:129]
	v_mfma_f32_16x16x32_bf16 v[122:125], v[182:185], v[190:193], v[122:125]
	v_mfma_f32_16x16x32_bf16 v[110:113], v[148:151], v[198:201], v[110:113]
	v_mfma_f32_16x16x32_bf16 v[106:109], v[182:185], v[198:201], v[106:109]
	v_mfma_f32_16x16x32_bf16 v[94:97], v[148:151], v[206:209], v[94:97]
	v_mfma_f32_16x16x32_bf16 v[90:93], v[182:185], v[206:209], v[90:93]
	v_mfma_f32_16x16x32_bf16 v[78:81], v[148:151], v[214:217], v[78:81]
	v_mfma_f32_16x16x32_bf16 v[74:77], v[182:185], v[214:217], v[74:77]
	s_barrier
	s_sub_u32 m0, s41, 0x80
	ds_read_b128 v[218:221], v173
	ds_read_b128 v[222:225], v174
	ds_read_b128 v[226:229], v175
	ds_read_b128 v[230:233], v176
	global_load_lds_dwordx4 v130, s[8:9] offset:128
	s_sub_u32 m0, s42, 0x80
	s_nop 0
	global_load_lds_dwordx4 v132, s[8:9] offset:128
	s_barrier
	s_waitcnt lgkmcnt(0)
	s_waitcnt lgkmcnt(0)
	v_mfma_f32_16x16x32_bf16 v[118:121], v[218:221], v[186:189], v[118:121]
	v_mfma_f32_16x16x32_bf16 v[114:117], v[226:229], v[186:189], v[114:117]
	v_mfma_f32_16x16x32_bf16 v[102:105], v[218:221], v[194:197], v[102:105]
	v_mfma_f32_16x16x32_bf16 v[98:101], v[226:229], v[194:197], v[98:101]
	v_mfma_f32_16x16x32_bf16 v[86:89], v[218:221], v[202:205], v[86:89]
	v_mfma_f32_16x16x32_bf16 v[82:85], v[226:229], v[202:205], v[82:85]
	v_mfma_f32_16x16x32_bf16 v[70:73], v[218:221], v[210:213], v[70:73]
	v_mfma_f32_16x16x32_bf16 v[66:69], v[226:229], v[210:213], v[66:69]
	v_mfma_f32_16x16x32_bf16 v[118:121], v[222:225], v[190:193], v[118:121]
	v_mfma_f32_16x16x32_bf16 v[114:117], v[230:233], v[190:193], v[114:117]
	v_mfma_f32_16x16x32_bf16 v[102:105], v[222:225], v[198:201], v[102:105]
	v_mfma_f32_16x16x32_bf16 v[98:101], v[230:233], v[198:201], v[98:101]
	v_mfma_f32_16x16x32_bf16 v[86:89], v[222:225], v[206:209], v[86:89]
	v_mfma_f32_16x16x32_bf16 v[82:85], v[230:233], v[206:209], v[82:85]
	v_mfma_f32_16x16x32_bf16 v[70:73], v[222:225], v[214:217], v[70:73]
	v_mfma_f32_16x16x32_bf16 v[66:69], v[230:233], v[214:217], v[66:69]
	s_sub_u32 m0, s43, 0x80
	s_barrier
	ds_read_b128 v[186:189], v158 offset:49152
	ds_read_b128 v[190:193], v158 offset:50176
	ds_read_b128 v[194:197], v158 offset:51200
	ds_read_b128 v[198:201], v158 offset:52224
	ds_read_b128 v[202:205], v158 offset:53248
	ds_read_b128 v[206:209], v158 offset:54272
	ds_read_b128 v[210:213], v158 offset:55296
	ds_read_b128 v[214:217], v158 offset:56320
	global_load_lds_dwordx4 v130, s[2:3] offset:128
	s_sub_u32 m0, s48, 0x80
	s_nop 0
	global_load_lds_dwordx4 v132, s[2:3] offset:128
	s_barrier
	s_waitcnt lgkmcnt(0)
	s_waitcnt lgkmcnt(0)
	v_mfma_f32_16x16x32_bf16 v[62:65], v[144:147], v[186:189], v[62:65]
	v_mfma_f32_16x16x32_bf16 v[58:61], v[178:181], v[186:189], v[58:61]
	v_mfma_f32_16x16x32_bf16 v[46:49], v[144:147], v[194:197], v[46:49]
	v_mfma_f32_16x16x32_bf16 v[42:45], v[178:181], v[194:197], v[42:45]
	v_mfma_f32_16x16x32_bf16 v[30:33], v[144:147], v[202:205], v[30:33]
	v_mfma_f32_16x16x32_bf16 v[26:29], v[178:181], v[202:205], v[26:29]
	v_mfma_f32_16x16x32_bf16 v[14:17], v[144:147], v[210:213], v[14:17]
	v_mfma_f32_16x16x32_bf16 v[10:13], v[178:181], v[210:213], v[10:13]
	v_mfma_f32_16x16x32_bf16 v[62:65], v[148:151], v[190:193], v[62:65]
	v_mfma_f32_16x16x32_bf16 v[58:61], v[182:185], v[190:193], v[58:61]
	v_mfma_f32_16x16x32_bf16 v[46:49], v[148:151], v[198:201], v[46:49]
	v_mfma_f32_16x16x32_bf16 v[42:45], v[182:185], v[198:201], v[42:45]
	v_mfma_f32_16x16x32_bf16 v[30:33], v[148:151], v[206:209], v[30:33]
	v_mfma_f32_16x16x32_bf16 v[26:29], v[182:185], v[206:209], v[26:29]
	v_mfma_f32_16x16x32_bf16 v[14:17], v[148:151], v[214:217], v[14:17]
	v_mfma_f32_16x16x32_bf16 v[10:13], v[182:185], v[214:217], v[10:13]
	s_barrier
	s_sub_u32 m0, s49, 0x80
	s_nop 0
	global_load_lds_dwordx4 v243, s[8:9] offset:128
	s_sub_u32 m0, s50, 0x80
	s_nop 0
	global_load_lds_dwordx4 v242, s[8:9] offset:128
	s_waitcnt vmcnt(6)
	s_barrier
	v_mfma_f32_16x16x32_bf16 v[54:57], v[218:221], v[186:189], v[54:57]
	v_mfma_f32_16x16x32_bf16 v[50:53], v[226:229], v[186:189], v[50:53]
	v_mfma_f32_16x16x32_bf16 v[38:41], v[218:221], v[194:197], v[38:41]
	v_mfma_f32_16x16x32_bf16 v[34:37], v[226:229], v[194:197], v[34:37]
	v_mfma_f32_16x16x32_bf16 v[22:25], v[218:221], v[202:205], v[22:25]
	v_mfma_f32_16x16x32_bf16 v[18:21], v[226:229], v[202:205], v[18:21]
	v_mfma_f32_16x16x32_bf16 v[6:9], v[218:221], v[210:213], v[6:9]
	v_mfma_f32_16x16x32_bf16 v[2:5], v[226:229], v[210:213], v[2:5]
	v_mfma_f32_16x16x32_bf16 v[54:57], v[222:225], v[190:193], v[54:57]
	v_mfma_f32_16x16x32_bf16 v[50:53], v[230:233], v[190:193], v[50:53]
	v_mfma_f32_16x16x32_bf16 v[38:41], v[222:225], v[198:201], v[38:41]
	v_mfma_f32_16x16x32_bf16 v[34:37], v[230:233], v[198:201], v[34:37]
	v_mfma_f32_16x16x32_bf16 v[22:25], v[222:225], v[206:209], v[22:25]
	v_mfma_f32_16x16x32_bf16 v[18:21], v[230:233], v[206:209], v[18:21]
	v_mfma_f32_16x16x32_bf16 v[6:9], v[222:225], v[214:217], v[6:9]
	v_mfma_f32_16x16x32_bf16 v[2:5], v[230:233], v[214:217], v[2:5]
	s_add_u32 s6, s6, 0x100
	s_addc_u32 s7, s7, 0
	s_add_u32 s10, s10, 0x100
	s_addc_u32 s11, s11, 0
	s_cmp_ge_i32 s14, s51
	s_mov_b32 s2, s14
	s_barrier
	s_cbranch_scc0 .LBB0_236

.LBB0_995:
	v_mov_b32_e32 v129, 0
	s_and_b64 vcc, exec, s[6:7]
	v_mov_b32_e32 v128, v129
	v_mov_b32_e32 v127, v129
	v_mov_b32_e32 v126, v129
	v_mov_b32_e32 v125, v129
	v_mov_b32_e32 v124, v129
	v_mov_b32_e32 v123, v129
	v_mov_b32_e32 v122, v129
	v_mov_b32_e32 v113, v129
	v_mov_b32_e32 v112, v129
	v_mov_b32_e32 v111, v129
	v_mov_b32_e32 v110, v129
	v_mov_b32_e32 v109, v129
	v_mov_b32_e32 v108, v129
	v_mov_b32_e32 v107, v129
	v_mov_b32_e32 v106, v129
	v_mov_b32_e32 v97, v129
	v_mov_b32_e32 v96, v129
	v_mov_b32_e32 v95, v129
	v_mov_b32_e32 v94, v129
	v_mov_b32_e32 v93, v129
	v_mov_b32_e32 v92, v129
	v_mov_b32_e32 v91, v129
	v_mov_b32_e32 v90, v129
	v_mov_b32_e32 v81, v129
	v_mov_b32_e32 v80, v129
	v_mov_b32_e32 v79, v129
	v_mov_b32_e32 v78, v129
	v_mov_b32_e32 v77, v129
	v_mov_b32_e32 v76, v129
	v_mov_b32_e32 v75, v129
	v_mov_b32_e32 v74, v129
	v_mov_b32_e32 v121, v129
	v_mov_b32_e32 v120, v129
	v_mov_b32_e32 v119, v129
	v_mov_b32_e32 v118, v129
	v_mov_b32_e32 v117, v129
	v_mov_b32_e32 v116, v129
	v_mov_b32_e32 v115, v129
	v_mov_b32_e32 v114, v129
	v_mov_b32_e32 v105, v129
	v_mov_b32_e32 v104, v129
	v_mov_b32_e32 v103, v129
	v_mov_b32_e32 v102, v129
	v_mov_b32_e32 v101, v129
	v_mov_b32_e32 v100, v129
	v_mov_b32_e32 v99, v129
	v_mov_b32_e32 v98, v129
	v_mov_b32_e32 v89, v129
	v_mov_b32_e32 v88, v129
	v_mov_b32_e32 v87, v129
	v_mov_b32_e32 v86, v129
	v_mov_b32_e32 v85, v129
	v_mov_b32_e32 v84, v129
	v_mov_b32_e32 v83, v129
	v_mov_b32_e32 v82, v129
	v_mov_b32_e32 v73, v129
	v_mov_b32_e32 v72, v129
	v_mov_b32_e32 v71, v129
	v_mov_b32_e32 v70, v129
	v_mov_b32_e32 v69, v129
	v_mov_b32_e32 v68, v129
	v_mov_b32_e32 v67, v129
	v_mov_b32_e32 v66, v129
	v_mov_b32_e32 v65, v129
	v_mov_b32_e32 v64, v129
	v_mov_b32_e32 v63, v129
	v_mov_b32_e32 v62, v129
	v_mov_b32_e32 v61, v129
	v_mov_b32_e32 v60, v129
	v_mov_b32_e32 v59, v129
	v_mov_b32_e32 v58, v129
	v_mov_b32_e32 v49, v129
	v_mov_b32_e32 v48, v129
	v_mov_b32_e32 v47, v129
	v_mov_b32_e32 v46, v129
	v_mov_b32_e32 v45, v129
	v_mov_b32_e32 v44, v129
	v_mov_b32_e32 v43, v129
	v_mov_b32_e32 v42, v129
	v_mov_b32_e32 v33, v129
	v_mov_b32_e32 v32, v129
	v_mov_b32_e32 v31, v129
	v_mov_b32_e32 v30, v129
	v_mov_b32_e32 v29, v129
	v_mov_b32_e32 v28, v129
	v_mov_b32_e32 v27, v129
	v_mov_b32_e32 v26, v129
	v_mov_b32_e32 v17, v129
	v_mov_b32_e32 v16, v129
	v_mov_b32_e32 v15, v129
	v_mov_b32_e32 v14, v129
	v_mov_b32_e32 v13, v129
	v_mov_b32_e32 v12, v129
	v_mov_b32_e32 v11, v129
	v_mov_b32_e32 v10, v129
	v_mov_b32_e32 v57, v129
	v_mov_b32_e32 v56, v129
	v_mov_b32_e32 v55, v129
	v_mov_b32_e32 v54, v129
	v_mov_b32_e32 v53, v129
	v_mov_b32_e32 v52, v129
	v_mov_b32_e32 v51, v129
	v_mov_b32_e32 v50, v129
	v_mov_b32_e32 v41, v129
	v_mov_b32_e32 v40, v129
	v_mov_b32_e32 v39, v129
	v_mov_b32_e32 v38, v129
	v_mov_b32_e32 v37, v129
	v_mov_b32_e32 v36, v129
	v_mov_b32_e32 v35, v129
	v_mov_b32_e32 v34, v129
	v_mov_b32_e32 v25, v129
	v_mov_b32_e32 v24, v129
	v_mov_b32_e32 v23, v129
	v_mov_b32_e32 v22, v129
	v_mov_b32_e32 v21, v129
	v_mov_b32_e32 v20, v129
	v_mov_b32_e32 v19, v129
	v_mov_b32_e32 v18, v129
	v_mov_b32_e32 v9, v129
	v_mov_b32_e32 v8, v129
	v_mov_b32_e32 v7, v129
	v_mov_b32_e32 v6, v129
	s_waitcnt lgkmcnt(0)
	v_mov_b32_e32 v5, v129
	v_mov_b32_e32 v4, v129
	v_mov_b32_e32 v3, v129
	v_mov_b32_e32 v2, v129
	s_cbranch_vccnz .LBB0_998
	s_add_u32 s24, s24, 0x80
	s_addc_u32 s25, s25, 0
	s_add_u32 s36, s26, 0x100
	v_mov_b32_e32 v2, 0
	s_addc_u32 s37, s27, 0
	s_mov_b32 s2, 0
	v_mov_b32_e32 v3, v2
	v_mov_b32_e32 v4, v2
	v_mov_b32_e32 v5, v2
	v_mov_b32_e32 v6, v2
	v_mov_b32_e32 v7, v2
	v_mov_b32_e32 v8, v2
	v_mov_b32_e32 v9, v2
	v_mov_b32_e32 v18, v2
	v_mov_b32_e32 v19, v2
	v_mov_b32_e32 v20, v2
	v_mov_b32_e32 v21, v2
	v_mov_b32_e32 v22, v2
	v_mov_b32_e32 v23, v2
	v_mov_b32_e32 v24, v2
	v_mov_b32_e32 v25, v2
	v_mov_b32_e32 v34, v2
	v_mov_b32_e32 v35, v2
	v_mov_b32_e32 v36, v2
	v_mov_b32_e32 v37, v2
	v_mov_b32_e32 v38, v2
	v_mov_b32_e32 v39, v2
	v_mov_b32_e32 v40, v2
	v_mov_b32_e32 v41, v2
	v_mov_b32_e32 v50, v2
	v_mov_b32_e32 v51, v2
	v_mov_b32_e32 v52, v2
	v_mov_b32_e32 v53, v2
	v_mov_b32_e32 v54, v2
	v_mov_b32_e32 v55, v2
	v_mov_b32_e32 v56, v2
	v_mov_b32_e32 v57, v2
	v_mov_b32_e32 v10, v2
	v_mov_b32_e32 v11, v2
	v_mov_b32_e32 v12, v2
	v_mov_b32_e32 v13, v2
	v_mov_b32_e32 v14, v2
	v_mov_b32_e32 v15, v2
	v_mov_b32_e32 v16, v2
	v_mov_b32_e32 v17, v2
	v_mov_b32_e32 v26, v2
	v_mov_b32_e32 v27, v2
	v_mov_b32_e32 v28, v2
	v_mov_b32_e32 v29, v2
	v_mov_b32_e32 v30, v2
	v_mov_b32_e32 v31, v2
	v_mov_b32_e32 v32, v2
	v_mov_b32_e32 v33, v2
	v_mov_b32_e32 v42, v2
	v_mov_b32_e32 v43, v2
	v_mov_b32_e32 v44, v2
	v_mov_b32_e32 v45, v2
	v_mov_b32_e32 v46, v2
	v_mov_b32_e32 v47, v2
	v_mov_b32_e32 v48, v2
	v_mov_b32_e32 v49, v2
	v_mov_b32_e32 v58, v2
	v_mov_b32_e32 v59, v2
	v_mov_b32_e32 v60, v2
	v_mov_b32_e32 v61, v2
	v_mov_b32_e32 v62, v2
	v_mov_b32_e32 v63, v2
	v_mov_b32_e32 v64, v2
	v_mov_b32_e32 v65, v2
	v_mov_b32_e32 v66, v2
	v_mov_b32_e32 v67, v2
	v_mov_b32_e32 v68, v2
	v_mov_b32_e32 v69, v2
	v_mov_b32_e32 v70, v2
	v_mov_b32_e32 v71, v2
	v_mov_b32_e32 v72, v2
	v_mov_b32_e32 v73, v2
	v_mov_b32_e32 v82, v2
	v_mov_b32_e32 v83, v2
	v_mov_b32_e32 v84, v2
	v_mov_b32_e32 v85, v2
	v_mov_b32_e32 v86, v2
	v_mov_b32_e32 v87, v2
	v_mov_b32_e32 v88, v2
	v_mov_b32_e32 v89, v2
	v_mov_b32_e32 v98, v2
	v_mov_b32_e32 v99, v2
	v_mov_b32_e32 v100, v2
	v_mov_b32_e32 v101, v2
	v_mov_b32_e32 v102, v2
	v_mov_b32_e32 v103, v2
	v_mov_b32_e32 v104, v2
	v_mov_b32_e32 v105, v2
	v_mov_b32_e32 v114, v2
	v_mov_b32_e32 v115, v2
	v_mov_b32_e32 v116, v2
	v_mov_b32_e32 v117, v2
	v_mov_b32_e32 v118, v2
	v_mov_b32_e32 v119, v2
	v_mov_b32_e32 v120, v2
	v_mov_b32_e32 v121, v2
	v_mov_b32_e32 v74, v2
	v_mov_b32_e32 v75, v2
	v_mov_b32_e32 v76, v2
	v_mov_b32_e32 v77, v2
	v_mov_b32_e32 v78, v2
	v_mov_b32_e32 v79, v2
	v_mov_b32_e32 v80, v2
	v_mov_b32_e32 v81, v2
	v_mov_b32_e32 v90, v2
	v_mov_b32_e32 v91, v2
	v_mov_b32_e32 v92, v2
	v_mov_b32_e32 v93, v2
	v_mov_b32_e32 v94, v2
	v_mov_b32_e32 v95, v2
	v_mov_b32_e32 v96, v2
	v_mov_b32_e32 v97, v2
	v_mov_b32_e32 v106, v2
	v_mov_b32_e32 v107, v2
	v_mov_b32_e32 v108, v2
	v_mov_b32_e32 v109, v2
	v_mov_b32_e32 v110, v2
	v_mov_b32_e32 v111, v2
	v_mov_b32_e32 v112, v2
	v_mov_b32_e32 v113, v2
	v_mov_b32_e32 v122, v2
	v_mov_b32_e32 v123, v2
	v_mov_b32_e32 v124, v2
	v_mov_b32_e32 v125, v2
	v_mov_b32_e32 v126, v2
	v_mov_b32_e32 v127, v2
	v_mov_b32_e32 v128, v2
	v_mov_b32_e32 v129, v2
	v_add_u32_e32 v243, s16, v130
	v_add_u32_e32 v242, s16, v132
.LBB0_997:
	ds_read_b128 v[142:145], v168
	ds_read_b128 v[146:149], v169
	ds_read_b128 v[150:153], v170
	ds_read_b128 v[154:157], v171
	s_add_i32 s57, s2, 2
	s_add_u32 s26, s24, 0x80
	s_addc_u32 s3, s25, 0
	s_cmp_eq_u32 s46, s2
	s_cselect_b32 s2, s10, s26
	s_cselect_b32 s3, s11, s3
	s_cselect_b32 s27, s1, s37
	s_cselect_b32 s26, s0, s36
	s_mov_b32 m0, s51
	ds_read_b128 v[186:189], v166
	ds_read_b128 v[190:193], v166 offset:1024
	ds_read_b128 v[194:197], v166 offset:2048
	ds_read_b128 v[198:201], v166 offset:3072
	ds_read_b128 v[202:205], v166 offset:4096
	ds_read_b128 v[206:209], v166 offset:5120
	ds_read_b128 v[210:213], v166 offset:6144
	ds_read_b128 v[214:217], v166 offset:7168
	global_load_lds_dwordx4 v134, s[24:25]
	s_mov_b32 m0, s52
	s_nop 0
	global_load_lds_dwordx4 v136, s[24:25]
	s_waitcnt lgkmcnt(8)
	s_barrier
	s_waitcnt lgkmcnt(0)
	s_waitcnt lgkmcnt(0)
	v_mfma_f32_16x16x32_bf16 v[126:129], v[142:145], v[186:189], v[126:129]
	v_mfma_f32_16x16x32_bf16 v[122:125], v[150:153], v[186:189], v[122:125]
	v_mfma_f32_16x16x32_bf16 v[110:113], v[142:145], v[194:197], v[110:113]
	v_mfma_f32_16x16x32_bf16 v[106:109], v[150:153], v[194:197], v[106:109]
	v_mfma_f32_16x16x32_bf16 v[94:97], v[142:145], v[202:205], v[94:97]
	v_mfma_f32_16x16x32_bf16 v[90:93], v[150:153], v[202:205], v[90:93]
	v_mfma_f32_16x16x32_bf16 v[78:81], v[142:145], v[210:213], v[78:81]
	v_mfma_f32_16x16x32_bf16 v[74:77], v[150:153], v[210:213], v[74:77]
	v_mfma_f32_16x16x32_bf16 v[126:129], v[146:149], v[190:193], v[126:129]
	v_mfma_f32_16x16x32_bf16 v[122:125], v[154:157], v[190:193], v[122:125]
	v_mfma_f32_16x16x32_bf16 v[110:113], v[146:149], v[198:201], v[110:113]
	v_mfma_f32_16x16x32_bf16 v[106:109], v[154:157], v[198:201], v[106:109]
	v_mfma_f32_16x16x32_bf16 v[94:97], v[146:149], v[206:209], v[94:97]
	v_mfma_f32_16x16x32_bf16 v[90:93], v[154:157], v[206:209], v[90:93]
	v_mfma_f32_16x16x32_bf16 v[78:81], v[146:149], v[214:217], v[78:81]
	v_mfma_f32_16x16x32_bf16 v[74:77], v[154:157], v[214:217], v[74:77]
	s_barrier
	s_mov_b32 m0, s29
	ds_read_b128 v[218:221], v172
	ds_read_b128 v[222:225], v173
	ds_read_b128 v[226:229], v174
	ds_read_b128 v[230:233], v175
	global_load_lds_dwordx4 v130, s[26:27]
	s_mov_b32 m0, s30
	s_nop 0
	global_load_lds_dwordx4 v132, s[26:27]
	s_barrier
	s_waitcnt lgkmcnt(0)
	s_waitcnt lgkmcnt(0)
	v_mfma_f32_16x16x32_bf16 v[118:121], v[218:221], v[186:189], v[118:121]
	v_mfma_f32_16x16x32_bf16 v[114:117], v[226:229], v[186:189], v[114:117]
	v_mfma_f32_16x16x32_bf16 v[102:105], v[218:221], v[194:197], v[102:105]
	v_mfma_f32_16x16x32_bf16 v[98:101], v[226:229], v[194:197], v[98:101]
	v_mfma_f32_16x16x32_bf16 v[86:89], v[218:221], v[202:205], v[86:89]
	v_mfma_f32_16x16x32_bf16 v[82:85], v[226:229], v[202:205], v[82:85]
	v_mfma_f32_16x16x32_bf16 v[70:73], v[218:221], v[210:213], v[70:73]
	v_mfma_f32_16x16x32_bf16 v[66:69], v[226:229], v[210:213], v[66:69]
	v_mfma_f32_16x16x32_bf16 v[118:121], v[222:225], v[190:193], v[118:121]
	v_mfma_f32_16x16x32_bf16 v[114:117], v[230:233], v[190:193], v[114:117]
	v_mfma_f32_16x16x32_bf16 v[102:105], v[222:225], v[198:201], v[102:105]
	v_mfma_f32_16x16x32_bf16 v[98:101], v[230:233], v[198:201], v[98:101]
	v_mfma_f32_16x16x32_bf16 v[86:89], v[222:225], v[206:209], v[86:89]
	v_mfma_f32_16x16x32_bf16 v[82:85], v[230:233], v[206:209], v[82:85]
	v_mfma_f32_16x16x32_bf16 v[70:73], v[222:225], v[214:217], v[70:73]
	v_mfma_f32_16x16x32_bf16 v[66:69], v[230:233], v[214:217], v[66:69]
	s_mov_b32 m0, s28
	s_barrier
	ds_read_b128 v[186:189], v166 offset:16384
	ds_read_b128 v[190:193], v166 offset:17408
	ds_read_b128 v[194:197], v166 offset:18432
	ds_read_b128 v[198:201], v166 offset:19456
	ds_read_b128 v[202:205], v166 offset:20480
	ds_read_b128 v[206:209], v166 offset:21504
	ds_read_b128 v[210:213], v166 offset:22528
	ds_read_b128 v[214:217], v166 offset:23552
	global_load_lds_dwordx4 v130, s[2:3]
	s_mov_b32 m0, s31
	s_nop 0
	global_load_lds_dwordx4 v132, s[2:3]
	s_barrier
	s_waitcnt lgkmcnt(0)
	s_waitcnt lgkmcnt(0)
	v_mfma_f32_16x16x32_bf16 v[62:65], v[142:145], v[186:189], v[62:65]
	v_mfma_f32_16x16x32_bf16 v[58:61], v[150:153], v[186:189], v[58:61]
	v_mfma_f32_16x16x32_bf16 v[46:49], v[142:145], v[194:197], v[46:49]
	v_mfma_f32_16x16x32_bf16 v[42:45], v[150:153], v[194:197], v[42:45]
	v_mfma_f32_16x16x32_bf16 v[30:33], v[142:145], v[202:205], v[30:33]
	v_mfma_f32_16x16x32_bf16 v[26:29], v[150:153], v[202:205], v[26:29]
	v_mfma_f32_16x16x32_bf16 v[14:17], v[142:145], v[210:213], v[14:17]
	v_mfma_f32_16x16x32_bf16 v[10:13], v[150:153], v[210:213], v[10:13]
	v_mfma_f32_16x16x32_bf16 v[62:65], v[146:149], v[190:193], v[62:65]
	v_mfma_f32_16x16x32_bf16 v[58:61], v[154:157], v[190:193], v[58:61]
	v_mfma_f32_16x16x32_bf16 v[46:49], v[146:149], v[198:201], v[46:49]
	v_mfma_f32_16x16x32_bf16 v[42:45], v[154:157], v[198:201], v[42:45]
	v_mfma_f32_16x16x32_bf16 v[30:33], v[146:149], v[206:209], v[30:33]
	v_mfma_f32_16x16x32_bf16 v[26:29], v[154:157], v[206:209], v[26:29]
	v_mfma_f32_16x16x32_bf16 v[14:17], v[146:149], v[214:217], v[14:17]
	v_mfma_f32_16x16x32_bf16 v[10:13], v[154:157], v[214:217], v[10:13]
	s_barrier
	s_mov_b32 m0, s33
	s_nop 0
	global_load_lds_dwordx4 v243, s[26:27]
	s_mov_b32 m0, s34
	s_nop 0
	global_load_lds_dwordx4 v242, s[26:27]
	s_waitcnt vmcnt(6)
	s_barrier
	v_mfma_f32_16x16x32_bf16 v[54:57], v[218:221], v[186:189], v[54:57]
	v_mfma_f32_16x16x32_bf16 v[50:53], v[226:229], v[186:189], v[50:53]
	v_mfma_f32_16x16x32_bf16 v[38:41], v[218:221], v[194:197], v[38:41]
	v_mfma_f32_16x16x32_bf16 v[34:37], v[226:229], v[194:197], v[34:37]
	v_mfma_f32_16x16x32_bf16 v[22:25], v[218:221], v[202:205], v[22:25]
	v_mfma_f32_16x16x32_bf16 v[18:21], v[226:229], v[202:205], v[18:21]
	v_mfma_f32_16x16x32_bf16 v[6:9], v[218:221], v[210:213], v[6:9]
	v_mfma_f32_16x16x32_bf16 v[2:5], v[226:229], v[210:213], v[2:5]
	v_mfma_f32_16x16x32_bf16 v[54:57], v[222:225], v[190:193], v[54:57]
	v_mfma_f32_16x16x32_bf16 v[50:53], v[230:233], v[190:193], v[50:53]
	v_mfma_f32_16x16x32_bf16 v[38:41], v[222:225], v[198:201], v[38:41]
	v_mfma_f32_16x16x32_bf16 v[34:37], v[230:233], v[198:201], v[34:37]
	v_mfma_f32_16x16x32_bf16 v[22:25], v[222:225], v[206:209], v[22:25]
	v_mfma_f32_16x16x32_bf16 v[18:21], v[230:233], v[206:209], v[18:21]
	v_mfma_f32_16x16x32_bf16 v[6:9], v[222:225], v[214:217], v[6:9]
	v_mfma_f32_16x16x32_bf16 v[2:5], v[230:233], v[214:217], v[2:5]
	s_barrier
	ds_read_b128 v[142:145], v176
	ds_read_b128 v[146:149], v177
	ds_read_b128 v[150:153], v178
	ds_read_b128 v[154:157], v179
	s_mov_b32 m0, s35
	ds_read_b128 v[186:189], v166 offset:32768
	ds_read_b128 v[190:193], v166 offset:33792
	ds_read_b128 v[194:197], v166 offset:34816
	ds_read_b128 v[198:201], v166 offset:35840
	ds_read_b128 v[202:205], v166 offset:36864
	ds_read_b128 v[206:209], v166 offset:37888
	ds_read_b128 v[210:213], v166 offset:38912
	ds_read_b128 v[214:217], v166 offset:39936
	global_load_lds_dwordx4 v243, s[2:3]
	s_mov_b32 m0, s38
	s_nop 0
	global_load_lds_dwordx4 v242, s[2:3]
	s_waitcnt lgkmcnt(8)
	s_barrier
	s_waitcnt lgkmcnt(0)
	s_waitcnt lgkmcnt(0)
	v_mfma_f32_16x16x32_bf16 v[126:129], v[142:145], v[186:189], v[126:129]
	v_mfma_f32_16x16x32_bf16 v[122:125], v[150:153], v[186:189], v[122:125]
	v_mfma_f32_16x16x32_bf16 v[110:113], v[142:145], v[194:197], v[110:113]
	v_mfma_f32_16x16x32_bf16 v[106:109], v[150:153], v[194:197], v[106:109]
	v_mfma_f32_16x16x32_bf16 v[94:97], v[142:145], v[202:205], v[94:97]
	v_mfma_f32_16x16x32_bf16 v[90:93], v[150:153], v[202:205], v[90:93]
	v_mfma_f32_16x16x32_bf16 v[78:81], v[142:145], v[210:213], v[78:81]
	v_mfma_f32_16x16x32_bf16 v[74:77], v[150:153], v[210:213], v[74:77]
	v_mfma_f32_16x16x32_bf16 v[126:129], v[146:149], v[190:193], v[126:129]
	v_mfma_f32_16x16x32_bf16 v[122:125], v[154:157], v[190:193], v[122:125]
	v_mfma_f32_16x16x32_bf16 v[110:113], v[146:149], v[198:201], v[110:113]
	v_mfma_f32_16x16x32_bf16 v[106:109], v[154:157], v[198:201], v[106:109]
	v_mfma_f32_16x16x32_bf16 v[94:97], v[146:149], v[206:209], v[94:97]
	v_mfma_f32_16x16x32_bf16 v[90:93], v[154:157], v[206:209], v[90:93]
	v_mfma_f32_16x16x32_bf16 v[78:81], v[146:149], v[214:217], v[78:81]
	v_mfma_f32_16x16x32_bf16 v[74:77], v[154:157], v[214:217], v[74:77]
	s_barrier
	s_sub_u32 m0, s39, 0x80
	ds_read_b128 v[218:221], v180
	ds_read_b128 v[222:225], v181
	ds_read_b128 v[226:229], v182
	ds_read_b128 v[230:233], v183
	global_load_lds_dwordx4 v130, s[26:27] offset:128
	s_sub_u32 m0, s40, 0x80
	s_nop 0
	global_load_lds_dwordx4 v132, s[26:27] offset:128
	s_barrier
	s_waitcnt lgkmcnt(0)
	s_waitcnt lgkmcnt(0)
	v_mfma_f32_16x16x32_bf16 v[118:121], v[218:221], v[186:189], v[118:121]
	v_mfma_f32_16x16x32_bf16 v[114:117], v[226:229], v[186:189], v[114:117]
	v_mfma_f32_16x16x32_bf16 v[102:105], v[218:221], v[194:197], v[102:105]
	v_mfma_f32_16x16x32_bf16 v[98:101], v[226:229], v[194:197], v[98:101]
	v_mfma_f32_16x16x32_bf16 v[86:89], v[218:221], v[202:205], v[86:89]
	v_mfma_f32_16x16x32_bf16 v[82:85], v[226:229], v[202:205], v[82:85]
	v_mfma_f32_16x16x32_bf16 v[70:73], v[218:221], v[210:213], v[70:73]
	v_mfma_f32_16x16x32_bf16 v[66:69], v[226:229], v[210:213], v[66:69]
	v_mfma_f32_16x16x32_bf16 v[118:121], v[222:225], v[190:193], v[118:121]
	v_mfma_f32_16x16x32_bf16 v[114:117], v[230:233], v[190:193], v[114:117]
	v_mfma_f32_16x16x32_bf16 v[102:105], v[222:225], v[198:201], v[102:105]
	v_mfma_f32_16x16x32_bf16 v[98:101], v[230:233], v[198:201], v[98:101]
	v_mfma_f32_16x16x32_bf16 v[86:89], v[222:225], v[206:209], v[86:89]
	v_mfma_f32_16x16x32_bf16 v[82:85], v[230:233], v[206:209], v[82:85]
	v_mfma_f32_16x16x32_bf16 v[70:73], v[222:225], v[214:217], v[70:73]
	v_mfma_f32_16x16x32_bf16 v[66:69], v[230:233], v[214:217], v[66:69]
	s_sub_u32 m0, s41, 0x80
	s_barrier
	ds_read_b128 v[186:189], v166 offset:49152
	ds_read_b128 v[190:193], v166 offset:50176
	ds_read_b128 v[194:197], v166 offset:51200
	ds_read_b128 v[198:201], v166 offset:52224
	ds_read_b128 v[202:205], v166 offset:53248
	ds_read_b128 v[206:209], v166 offset:54272
	ds_read_b128 v[210:213], v166 offset:55296
	ds_read_b128 v[214:217], v166 offset:56320
	global_load_lds_dwordx4 v130, s[2:3] offset:128
	s_sub_u32 m0, s42, 0x80
	s_nop 0
	global_load_lds_dwordx4 v132, s[2:3] offset:128
	s_barrier
	s_waitcnt lgkmcnt(0)
	s_waitcnt lgkmcnt(0)
	v_mfma_f32_16x16x32_bf16 v[62:65], v[142:145], v[186:189], v[62:65]
	v_mfma_f32_16x16x32_bf16 v[58:61], v[150:153], v[186:189], v[58:61]
	v_mfma_f32_16x16x32_bf16 v[46:49], v[142:145], v[194:197], v[46:49]
	v_mfma_f32_16x16x32_bf16 v[42:45], v[150:153], v[194:197], v[42:45]
	v_mfma_f32_16x16x32_bf16 v[30:33], v[142:145], v[202:205], v[30:33]
	v_mfma_f32_16x16x32_bf16 v[26:29], v[150:153], v[202:205], v[26:29]
	v_mfma_f32_16x16x32_bf16 v[14:17], v[142:145], v[210:213], v[14:17]
	v_mfma_f32_16x16x32_bf16 v[10:13], v[150:153], v[210:213], v[10:13]
	v_mfma_f32_16x16x32_bf16 v[62:65], v[146:149], v[190:193], v[62:65]
	v_mfma_f32_16x16x32_bf16 v[58:61], v[154:157], v[190:193], v[58:61]
	v_mfma_f32_16x16x32_bf16 v[46:49], v[146:149], v[198:201], v[46:49]
	v_mfma_f32_16x16x32_bf16 v[42:45], v[154:157], v[198:201], v[42:45]
	v_mfma_f32_16x16x32_bf16 v[30:33], v[146:149], v[206:209], v[30:33]
	v_mfma_f32_16x16x32_bf16 v[26:29], v[154:157], v[206:209], v[26:29]
	v_mfma_f32_16x16x32_bf16 v[14:17], v[146:149], v[214:217], v[14:17]
	v_mfma_f32_16x16x32_bf16 v[10:13], v[154:157], v[214:217], v[10:13]
	s_barrier
	s_sub_u32 m0, s43, 0x80
	s_nop 0
	global_load_lds_dwordx4 v243, s[26:27] offset:128
	s_sub_u32 m0, s44, 0x80
	s_nop 0
	global_load_lds_dwordx4 v242, s[26:27] offset:128
	s_waitcnt vmcnt(6)
	s_barrier
	v_mfma_f32_16x16x32_bf16 v[54:57], v[218:221], v[186:189], v[54:57]
	v_mfma_f32_16x16x32_bf16 v[50:53], v[226:229], v[186:189], v[50:53]
	v_mfma_f32_16x16x32_bf16 v[38:41], v[218:221], v[194:197], v[38:41]
	v_mfma_f32_16x16x32_bf16 v[34:37], v[226:229], v[194:197], v[34:37]
	v_mfma_f32_16x16x32_bf16 v[22:25], v[218:221], v[202:205], v[22:25]
	v_mfma_f32_16x16x32_bf16 v[18:21], v[226:229], v[202:205], v[18:21]
	v_mfma_f32_16x16x32_bf16 v[6:9], v[218:221], v[210:213], v[6:9]
	v_mfma_f32_16x16x32_bf16 v[2:5], v[226:229], v[210:213], v[2:5]
	v_mfma_f32_16x16x32_bf16 v[54:57], v[222:225], v[190:193], v[54:57]
	v_mfma_f32_16x16x32_bf16 v[50:53], v[230:233], v[190:193], v[50:53]
	v_mfma_f32_16x16x32_bf16 v[38:41], v[222:225], v[198:201], v[38:41]
	v_mfma_f32_16x16x32_bf16 v[34:37], v[230:233], v[198:201], v[34:37]
	v_mfma_f32_16x16x32_bf16 v[22:25], v[222:225], v[206:209], v[22:25]
	v_mfma_f32_16x16x32_bf16 v[18:21], v[230:233], v[206:209], v[18:21]
	v_mfma_f32_16x16x32_bf16 v[6:9], v[222:225], v[214:217], v[6:9]
	v_mfma_f32_16x16x32_bf16 v[2:5], v[230:233], v[214:217], v[2:5]
	s_add_u32 s24, s24, 0x100
	s_addc_u32 s25, s25, 0
	s_add_u32 s36, s36, 0x100
	s_addc_u32 s37, s37, 0
	s_cmp_ge_i32 s57, s45
	s_mov_b32 s2, s57
	s_barrier
	s_cbranch_scc0 .LBB0_997

.LBB0_1254:
	s_add_u32 s26, s58, 0x80
	s_addc_u32 s27, s59, 0
	s_add_u32 s37, s56, 0x100
	s_addc_u32 s53, s57, 0
	s_mov_b32 s2, 0
	v_add_u32_e32 v249, s20, v134
	v_add_u32_e32 v248, s20, v136
.LBB0_1255:
	ds_read_b128 v[146:149], v177
	ds_read_b128 v[150:153], v178
	ds_read_b128 v[154:157], v179
	ds_read_b128 v[158:161], v180
	s_add_i32 s72, s2, 2
	s_add_u32 s28, s26, 0x80
	s_addc_u32 s3, s27, 0
	s_cmp_eq_u32 s64, s2
	s_cselect_b32 s2, s54, s28
	s_cselect_b32 s3, s55, s3
	s_cselect_b32 s29, s1, s53
	s_cselect_b32 s28, s0, s37
	s_mov_b32 m0, s66
	ds_read_b128 v[164:167], v174
	ds_read_b128 v[168:171], v174 offset:1024
	ds_read_b128 v[194:197], v174 offset:2048
	ds_read_b128 v[198:201], v174 offset:3072
	ds_read_b128 v[206:209], v174 offset:4096
	ds_read_b128 v[210:213], v174 offset:5120
	ds_read_b128 v[214:217], v174 offset:6144
	ds_read_b128 v[218:221], v174 offset:7168
	global_load_lds_dwordx4 v138, s[26:27]
	s_mov_b32 m0, s67
	s_nop 0
	global_load_lds_dwordx4 v140, s[26:27]
	s_waitcnt lgkmcnt(8)
	s_barrier
	s_waitcnt lgkmcnt(0)
	s_waitcnt lgkmcnt(0)
	v_mfma_f32_16x16x32_bf16 v[130:133], v[146:149], v[164:167], v[130:133]
	v_mfma_f32_16x16x32_bf16 v[126:129], v[154:157], v[164:167], v[126:129]
	v_mfma_f32_16x16x32_bf16 v[114:117], v[146:149], v[194:197], v[114:117]
	v_mfma_f32_16x16x32_bf16 v[110:113], v[154:157], v[194:197], v[110:113]
	v_mfma_f32_16x16x32_bf16 v[98:101], v[146:149], v[206:209], v[98:101]
	v_mfma_f32_16x16x32_bf16 v[94:97], v[154:157], v[206:209], v[94:97]
	v_mfma_f32_16x16x32_bf16 v[82:85], v[146:149], v[214:217], v[82:85]
	v_mfma_f32_16x16x32_bf16 v[78:81], v[154:157], v[214:217], v[78:81]
	v_mfma_f32_16x16x32_bf16 v[130:133], v[150:153], v[168:171], v[130:133]
	v_mfma_f32_16x16x32_bf16 v[126:129], v[158:161], v[168:171], v[126:129]
	v_mfma_f32_16x16x32_bf16 v[114:117], v[150:153], v[198:201], v[114:117]
	v_mfma_f32_16x16x32_bf16 v[110:113], v[158:161], v[198:201], v[110:113]
	v_mfma_f32_16x16x32_bf16 v[98:101], v[150:153], v[210:213], v[98:101]
	v_mfma_f32_16x16x32_bf16 v[94:97], v[158:161], v[210:213], v[94:97]
	v_mfma_f32_16x16x32_bf16 v[82:85], v[150:153], v[218:221], v[82:85]
	v_mfma_f32_16x16x32_bf16 v[78:81], v[158:161], v[218:221], v[78:81]
	s_barrier
	s_mov_b32 m0, s38
	ds_read_b128 v[222:225], v181
	ds_read_b128 v[226:229], v182
	ds_read_b128 v[230:233], v183
	ds_read_b128 v[234:237], v184
	global_load_lds_dwordx4 v134, s[28:29]
	s_mov_b32 m0, s39
	s_nop 0
	global_load_lds_dwordx4 v136, s[28:29]
	s_barrier
	s_waitcnt lgkmcnt(0)
	s_waitcnt lgkmcnt(0)
	v_mfma_f32_16x16x32_bf16 v[122:125], v[222:225], v[164:167], v[122:125]
	v_mfma_f32_16x16x32_bf16 v[118:121], v[230:233], v[164:167], v[118:121]
	v_mfma_f32_16x16x32_bf16 v[106:109], v[222:225], v[194:197], v[106:109]
	v_mfma_f32_16x16x32_bf16 v[102:105], v[230:233], v[194:197], v[102:105]
	v_mfma_f32_16x16x32_bf16 v[90:93], v[222:225], v[206:209], v[90:93]
	v_mfma_f32_16x16x32_bf16 v[86:89], v[230:233], v[206:209], v[86:89]
	v_mfma_f32_16x16x32_bf16 v[74:77], v[222:225], v[214:217], v[74:77]
	v_mfma_f32_16x16x32_bf16 v[68:71], v[230:233], v[214:217], v[70:73]
	v_mfma_f32_16x16x32_bf16 v[122:125], v[226:229], v[168:171], v[122:125]
	v_mfma_f32_16x16x32_bf16 v[118:121], v[234:237], v[168:171], v[118:121]
	v_mfma_f32_16x16x32_bf16 v[106:109], v[226:229], v[198:201], v[106:109]
	v_mfma_f32_16x16x32_bf16 v[102:105], v[234:237], v[198:201], v[102:105]
	v_mfma_f32_16x16x32_bf16 v[90:93], v[226:229], v[210:213], v[90:93]
	v_mfma_f32_16x16x32_bf16 v[86:89], v[234:237], v[210:213], v[86:89]
	v_mfma_f32_16x16x32_bf16 v[74:77], v[226:229], v[218:221], v[74:77]
	v_mfma_f32_16x16x32_bf16 v[68:71], v[234:237], v[218:221], v[68:71]
	s_mov_b32 m0, s35
	s_barrier
	ds_read_b128 v[164:167], v174 offset:16384
	ds_read_b128 v[168:171], v174 offset:17408
	ds_read_b128 v[194:197], v174 offset:18432
	ds_read_b128 v[198:201], v174 offset:19456
	ds_read_b128 v[206:209], v174 offset:20480
	ds_read_b128 v[210:213], v174 offset:21504
	ds_read_b128 v[214:217], v174 offset:22528
	ds_read_b128 v[218:221], v174 offset:23552
	global_load_lds_dwordx4 v134, s[2:3]
	s_mov_b32 m0, s40
	s_nop 0
	global_load_lds_dwordx4 v136, s[2:3]
	s_barrier
	s_waitcnt lgkmcnt(0)
	s_waitcnt lgkmcnt(0)
	v_mfma_f32_16x16x32_bf16 v[62:65], v[146:149], v[164:167], v[62:65]
	v_mfma_f32_16x16x32_bf16 v[58:61], v[154:157], v[164:167], v[58:61]
	v_mfma_f32_16x16x32_bf16 v[46:49], v[146:149], v[194:197], v[46:49]
	v_mfma_f32_16x16x32_bf16 v[42:45], v[154:157], v[194:197], v[42:45]
	v_mfma_f32_16x16x32_bf16 v[30:33], v[146:149], v[206:209], v[30:33]
	v_mfma_f32_16x16x32_bf16 v[26:29], v[154:157], v[206:209], v[26:29]
	v_mfma_f32_16x16x32_bf16 v[14:17], v[146:149], v[214:217], v[14:17]
	v_mfma_f32_16x16x32_bf16 v[10:13], v[154:157], v[214:217], v[10:13]
	v_mfma_f32_16x16x32_bf16 v[62:65], v[150:153], v[168:171], v[62:65]
	v_mfma_f32_16x16x32_bf16 v[58:61], v[158:161], v[168:171], v[58:61]
	v_mfma_f32_16x16x32_bf16 v[46:49], v[150:153], v[198:201], v[46:49]
	v_mfma_f32_16x16x32_bf16 v[42:45], v[158:161], v[198:201], v[42:45]
	v_mfma_f32_16x16x32_bf16 v[30:33], v[150:153], v[210:213], v[30:33]
	v_mfma_f32_16x16x32_bf16 v[26:29], v[158:161], v[210:213], v[26:29]
	v_mfma_f32_16x16x32_bf16 v[14:17], v[150:153], v[218:221], v[14:17]
	v_mfma_f32_16x16x32_bf16 v[10:13], v[158:161], v[218:221], v[10:13]
	s_barrier
	s_mov_b32 m0, s41
	s_nop 0
	global_load_lds_dwordx4 v249, s[28:29]
	s_mov_b32 m0, s42
	s_nop 0
	global_load_lds_dwordx4 v248, s[28:29]
	s_waitcnt vmcnt(6)
	s_barrier
	v_mfma_f32_16x16x32_bf16 v[54:57], v[222:225], v[164:167], v[54:57]
	v_mfma_f32_16x16x32_bf16 v[50:53], v[230:233], v[164:167], v[50:53]
	v_mfma_f32_16x16x32_bf16 v[38:41], v[222:225], v[194:197], v[38:41]
	v_mfma_f32_16x16x32_bf16 v[34:37], v[230:233], v[194:197], v[34:37]
	v_mfma_f32_16x16x32_bf16 v[22:25], v[222:225], v[206:209], v[22:25]
	v_mfma_f32_16x16x32_bf16 v[18:21], v[230:233], v[206:209], v[18:21]
	v_mfma_f32_16x16x32_bf16 v[6:9], v[222:225], v[214:217], v[6:9]
	v_mfma_f32_16x16x32_bf16 v[2:5], v[230:233], v[214:217], v[2:5]
	v_mfma_f32_16x16x32_bf16 v[54:57], v[226:229], v[168:171], v[54:57]
	v_mfma_f32_16x16x32_bf16 v[50:53], v[234:237], v[168:171], v[50:53]
	v_mfma_f32_16x16x32_bf16 v[38:41], v[226:229], v[198:201], v[38:41]
	v_mfma_f32_16x16x32_bf16 v[34:37], v[234:237], v[198:201], v[34:37]
	v_mfma_f32_16x16x32_bf16 v[22:25], v[226:229], v[210:213], v[22:25]
	v_mfma_f32_16x16x32_bf16 v[18:21], v[234:237], v[210:213], v[18:21]
	v_mfma_f32_16x16x32_bf16 v[6:9], v[226:229], v[218:221], v[6:9]
	v_mfma_f32_16x16x32_bf16 v[2:5], v[234:237], v[218:221], v[2:5]
	s_barrier
	ds_read_b128 v[146:149], v185
	ds_read_b128 v[150:153], v186
	ds_read_b128 v[154:157], v187
	ds_read_b128 v[158:161], v188
	s_mov_b32 m0, s43
	ds_read_b128 v[164:167], v174 offset:32768
	ds_read_b128 v[168:171], v174 offset:33792
	ds_read_b128 v[194:197], v174 offset:34816
	ds_read_b128 v[198:201], v174 offset:35840
	ds_read_b128 v[206:209], v174 offset:36864
	ds_read_b128 v[210:213], v174 offset:37888
	ds_read_b128 v[214:217], v174 offset:38912
	ds_read_b128 v[218:221], v174 offset:39936
	global_load_lds_dwordx4 v249, s[2:3]
	s_mov_b32 m0, s45
	s_nop 0
	global_load_lds_dwordx4 v248, s[2:3]
	s_waitcnt lgkmcnt(8)
	s_barrier
	s_waitcnt lgkmcnt(0)
	s_waitcnt lgkmcnt(0)
	v_mfma_f32_16x16x32_bf16 v[130:133], v[146:149], v[164:167], v[130:133]
	v_mfma_f32_16x16x32_bf16 v[126:129], v[154:157], v[164:167], v[126:129]
	v_mfma_f32_16x16x32_bf16 v[114:117], v[146:149], v[194:197], v[114:117]
	v_mfma_f32_16x16x32_bf16 v[110:113], v[154:157], v[194:197], v[110:113]
	v_mfma_f32_16x16x32_bf16 v[98:101], v[146:149], v[206:209], v[98:101]
	v_mfma_f32_16x16x32_bf16 v[94:97], v[154:157], v[206:209], v[94:97]
	v_mfma_f32_16x16x32_bf16 v[82:85], v[146:149], v[214:217], v[82:85]
	v_mfma_f32_16x16x32_bf16 v[78:81], v[154:157], v[214:217], v[78:81]
	v_mfma_f32_16x16x32_bf16 v[130:133], v[150:153], v[168:171], v[130:133]
	v_mfma_f32_16x16x32_bf16 v[126:129], v[158:161], v[168:171], v[126:129]
	v_mfma_f32_16x16x32_bf16 v[114:117], v[150:153], v[198:201], v[114:117]
	v_mfma_f32_16x16x32_bf16 v[110:113], v[158:161], v[198:201], v[110:113]
	v_mfma_f32_16x16x32_bf16 v[98:101], v[150:153], v[210:213], v[98:101]
	v_mfma_f32_16x16x32_bf16 v[94:97], v[158:161], v[210:213], v[94:97]
	v_mfma_f32_16x16x32_bf16 v[82:85], v[150:153], v[218:221], v[82:85]
	v_mfma_f32_16x16x32_bf16 v[78:81], v[158:161], v[218:221], v[78:81]
	s_barrier
	s_sub_u32 m0, s50, 0x80
	ds_read_b128 v[222:225], v189
	ds_read_b128 v[226:229], v190
	ds_read_b128 v[230:233], v191
	ds_read_b128 v[234:237], v192
	global_load_lds_dwordx4 v134, s[28:29] offset:128
	s_sub_u32 m0, s51, 0x80
	s_nop 0
	global_load_lds_dwordx4 v136, s[28:29] offset:128
	s_barrier
	s_waitcnt lgkmcnt(0)
	s_waitcnt lgkmcnt(0)
	v_mfma_f32_16x16x32_bf16 v[122:125], v[222:225], v[164:167], v[122:125]
	v_mfma_f32_16x16x32_bf16 v[118:121], v[230:233], v[164:167], v[118:121]
	v_mfma_f32_16x16x32_bf16 v[106:109], v[222:225], v[194:197], v[106:109]
	v_mfma_f32_16x16x32_bf16 v[102:105], v[230:233], v[194:197], v[102:105]
	v_mfma_f32_16x16x32_bf16 v[90:93], v[222:225], v[206:209], v[90:93]
	v_mfma_f32_16x16x32_bf16 v[86:89], v[230:233], v[206:209], v[86:89]
	v_mfma_f32_16x16x32_bf16 v[72:75], v[222:225], v[214:217], v[74:77]
	v_mfma_f32_16x16x32_bf16 v[68:71], v[230:233], v[214:217], v[68:71]
	v_mfma_f32_16x16x32_bf16 v[122:125], v[226:229], v[168:171], v[122:125]
	v_mfma_f32_16x16x32_bf16 v[118:121], v[234:237], v[168:171], v[118:121]
	v_mfma_f32_16x16x32_bf16 v[106:109], v[226:229], v[198:201], v[106:109]
	v_mfma_f32_16x16x32_bf16 v[102:105], v[234:237], v[198:201], v[102:105]
	v_mfma_f32_16x16x32_bf16 v[90:93], v[226:229], v[210:213], v[90:93]
	v_mfma_f32_16x16x32_bf16 v[86:89], v[234:237], v[210:213], v[86:89]
	v_mfma_f32_16x16x32_bf16 v[74:77], v[226:229], v[218:221], v[72:75]
	v_mfma_f32_16x16x32_bf16 v[70:73], v[234:237], v[218:221], v[68:71]
	s_sub_u32 m0, s60, 0x80
	s_nop 0
	s_barrier
	ds_read_b128 v[164:167], v174 offset:49152
	ds_read_b128 v[168:171], v174 offset:50176
	ds_read_b128 v[194:197], v174 offset:51200
	ds_read_b128 v[198:201], v174 offset:52224
	ds_read_b128 v[206:209], v174 offset:53248
	ds_read_b128 v[210:213], v174 offset:54272
	ds_read_b128 v[214:217], v174 offset:55296
	ds_read_b128 v[218:221], v174 offset:56320
	global_load_lds_dwordx4 v134, s[2:3] offset:128
	s_sub_u32 m0, s61, 0x80
	s_nop 0
	global_load_lds_dwordx4 v136, s[2:3] offset:128
	s_barrier
	s_waitcnt lgkmcnt(0)
	s_waitcnt lgkmcnt(0)
	v_mfma_f32_16x16x32_bf16 v[62:65], v[146:149], v[164:167], v[62:65]
	v_mfma_f32_16x16x32_bf16 v[58:61], v[154:157], v[164:167], v[58:61]
	v_mfma_f32_16x16x32_bf16 v[46:49], v[146:149], v[194:197], v[46:49]
	v_mfma_f32_16x16x32_bf16 v[42:45], v[154:157], v[194:197], v[42:45]
	v_mfma_f32_16x16x32_bf16 v[30:33], v[146:149], v[206:209], v[30:33]
	v_mfma_f32_16x16x32_bf16 v[26:29], v[154:157], v[206:209], v[26:29]
	v_mfma_f32_16x16x32_bf16 v[14:17], v[146:149], v[214:217], v[14:17]
	v_mfma_f32_16x16x32_bf16 v[10:13], v[154:157], v[214:217], v[10:13]
	v_mfma_f32_16x16x32_bf16 v[62:65], v[150:153], v[168:171], v[62:65]
	v_mfma_f32_16x16x32_bf16 v[58:61], v[158:161], v[168:171], v[58:61]
	v_mfma_f32_16x16x32_bf16 v[46:49], v[150:153], v[198:201], v[46:49]
	v_mfma_f32_16x16x32_bf16 v[42:45], v[158:161], v[198:201], v[42:45]
	v_mfma_f32_16x16x32_bf16 v[30:33], v[150:153], v[210:213], v[30:33]
	v_mfma_f32_16x16x32_bf16 v[26:29], v[158:161], v[210:213], v[26:29]
	v_mfma_f32_16x16x32_bf16 v[14:17], v[150:153], v[218:221], v[14:17]
	v_mfma_f32_16x16x32_bf16 v[10:13], v[158:161], v[218:221], v[10:13]
	s_barrier
	s_sub_u32 m0, s62, 0x80
	s_nop 0
	global_load_lds_dwordx4 v249, s[28:29] offset:128
	s_sub_u32 m0, s63, 0x80
	s_nop 0
	global_load_lds_dwordx4 v248, s[28:29] offset:128
	s_waitcnt vmcnt(6)
	s_barrier
	v_mfma_f32_16x16x32_bf16 v[54:57], v[222:225], v[164:167], v[54:57]
	v_mfma_f32_16x16x32_bf16 v[50:53], v[230:233], v[164:167], v[50:53]
	v_mfma_f32_16x16x32_bf16 v[38:41], v[222:225], v[194:197], v[38:41]
	v_mfma_f32_16x16x32_bf16 v[34:37], v[230:233], v[194:197], v[34:37]
	v_mfma_f32_16x16x32_bf16 v[22:25], v[222:225], v[206:209], v[22:25]
	v_mfma_f32_16x16x32_bf16 v[18:21], v[230:233], v[206:209], v[18:21]
	v_mfma_f32_16x16x32_bf16 v[6:9], v[222:225], v[214:217], v[6:9]
	v_mfma_f32_16x16x32_bf16 v[2:5], v[230:233], v[214:217], v[2:5]
	v_mfma_f32_16x16x32_bf16 v[54:57], v[226:229], v[168:171], v[54:57]
	v_mfma_f32_16x16x32_bf16 v[50:53], v[234:237], v[168:171], v[50:53]
	v_mfma_f32_16x16x32_bf16 v[38:41], v[226:229], v[198:201], v[38:41]
	v_mfma_f32_16x16x32_bf16 v[34:37], v[234:237], v[198:201], v[34:37]
	v_mfma_f32_16x16x32_bf16 v[22:25], v[226:229], v[210:213], v[22:25]
	v_mfma_f32_16x16x32_bf16 v[18:21], v[234:237], v[210:213], v[18:21]
	v_mfma_f32_16x16x32_bf16 v[6:9], v[226:229], v[218:221], v[6:9]
	v_mfma_f32_16x16x32_bf16 v[2:5], v[234:237], v[218:221], v[2:5]
	s_add_u32 s26, s26, 0x100
	s_addc_u32 s27, s27, 0
	s_add_u32 s37, s37, 0x100
	s_addc_u32 s53, s53, 0
	s_cmp_ge_i32 s72, s49
	s_mov_b32 s2, s72
	s_barrier
	s_cbranch_scc0 .LBB0_1255
